# P8 FFN-up: sample-row tiles split into two half-K units (fills the 12th round; two f32 partial buffers summed in P9), own tile decode
# speedup vs baseline: 1.0047x; 1.0047x over previous
.LBB0_1088:
	s_waitcnt vmcnt(0)
	v_and_b32_e32 v10, 0x3ff, v0
	s_cmpk_lt_i32 s3, 0xb58
	s_cselect_b64 s[4:5], -1, 0
	s_cmpk_gt_i32 s3, 0xb57
	v_readfirstlane_b32 s54, v10
	s_cbranch_scc1 .LBB0_1090
	s_and_b32 s46, s3, 7
	s_mulk_i32 s46, 0x160
	s_lshr_b32 s6, s3, 3
	s_add_i32 s46, s46, s6
	s_lshr_b32 s6, s46, 3
	s_mul_hi_u32 s6, s6, 0xba2e8ba3
	s_lshr_b32 s6, s6, 3
	s_mul_i32 s7, s6, 0x58
	s_sub_i32 s46, s46, s7
	s_lshl_b32 s6, s6, 1
	s_and_b32 s7, s46, 1
	s_add_i32 s20, s6, s7
	s_lshr_b32 s46, s46, 1

.LBB0_1093:
	s_lshl_b32 s4, s4, 5
	s_and_b32 s10, s4, 0x60
	s_lshl_b32 s6, s55, 13
	s_lshl_b32 s7, s10, 7
	s_add_u32 s22, s18, 0xa5b8000
	s_addc_u32 s23, s19, 0
	s_add_u32 s24, s18, 0x15b38000
	s_addc_u32 s25, s19, 0
	s_add_u32 s26, s18, 0x17138000
	s_addc_u32 s27, s19, 0
	s_add_u32 s28, s18, 0x18738000
	s_addc_u32 s29, s19, 0
	s_ashr_i32 s63, s33, 31
	s_add_u32 s30, s12, 0xb000
	s_addc_u32 s31, s13, 0
	s_add_u32 s34, s12, 0x16000
	s_mov_b64 s[36:37], 0x80
	s_addc_u32 s35, s13, 0
	s_add_i32 m0, s21, 0x18000
	v_lshl_add_u64 v[8:9], v[8:9], 0, s[36:37]
	s_waitcnt vmcnt(4)
	s_barrier
	global_load_lds_dwordx4 v[8:9], off
	v_lshl_add_u64 v[6:7], v[6:7], 0, s[36:37]
	s_add_i32 m0, s21, 0x1a000
	s_add_i32 s64, s21, 0x8000
	s_add_i32 s65, s21, 0xa000
	global_load_lds_dwordx4 v[6:7], off
	v_lshl_add_u64 v[4:5], v[4:5], 0, s[36:37]
	s_mov_b32 m0, s64
	s_add_u32 s4, s50, 0x80080
	global_load_lds_dwordx4 v[4:5], off
	v_lshl_add_u64 v[2:3], v[2:3], 0, s[36:37]
	s_mov_b32 m0, s65
	s_addc_u32 s5, s51, 0
	global_load_lds_dwordx4 v[2:3], off
	s_add_i32 m0, s21, 0x1c000
	v_lshl_add_u64 v[2:3], s[4:5], 0, v[162:163]
	global_load_lds_dwordx4 v[2:3], off
	v_lshl_add_u64 v[2:3], s[4:5], 0, v[164:165]
	s_add_i32 m0, s21, 0x1e000
	v_lshlrev_b32_e32 v4, 6, v10
	global_load_lds_dwordx4 v[2:3], off
	v_bfe_u32 v2, v10, 4, 2
	v_lshlrev_b32_e32 v3, 4, v2
	s_movk_i32 s4, 0x3c0
	v_lshlrev_b32_e32 v5, 2, v10
	v_and_or_b32 v4, v4, s4, v3
	v_and_b32_e32 v5, 32, v5
	v_lshl_or_b32 v239, v2, 2, s10
	v_lshlrev_b32_e32 v2, 9, v10
	v_bitop3_b32 v236, s7, v4, v5 bitop3:0xf6
	v_and_b32_e32 v2, 0x70000, v2
	v_lshlrev_b32_e32 v4, 12, v13
	v_or3_b32 v2, v11, v2, v4
	v_and_b32_e32 v1, 15, v10
	v_add_u32_e32 v166, v2, v12
	v_lshlrev_b32_e32 v2, 5, v14
	v_lshl_or_b32 v3, v1, 6, v3
	s_waitcnt vmcnt(6)
	v_and_b32_e32 v2, 0xf0000, v2
	v_lshl_or_b32 v6, s55, 6, v1
	v_bitop3_b32 v3, v3, s6, v5 bitop3:0xde
	v_or3_b32 v2, v11, v2, v4
	s_add_i32 s68, 0, 0x10000
	s_add_i32 s69, 0, 0x14000
	v_cmp_gt_u32_e64 s[4:5], 2, v1
	v_cmp_lt_u32_e64 s[6:7], 13, v1
	v_add_u32_e32 v237, -14, v1
	v_cmp_lt_u32_e64 s[8:9], 1, v1
	v_add_u32_e32 v238, 0xffffc000, v6
	s_ashr_i32 s66, s3, 31
	v_mov_b32_e32 v167, v163
	v_add_u32_e32 v170, v2, v12
	v_mov_b32_e32 v171, v163
	v_mov_b64_e32 v[172:173], 0xbb0
	v_mov_b64_e32 v[174:175], 0xbaf
	s_movk_i32 s67, 0x16c
	s_mov_b32 s87, 28
	v_add_u32_e32 v240, s68, v236
	v_add_u32_e32 v241, 0, v3
	v_add_u32_e32 v242, s69, v236
	s_movk_i32 s70, 0x5000
	s_mov_b32 s71, 0xb000
	s_movk_i32 s72, 0x2c00
	s_barrier
	s_branch .LBB0_1095
.LBB0_1094:
	s_and_b64 vcc, exec, s[10:11]
	s_mov_b32 s46, s38
	s_mov_b32 s20, s40
	s_mov_b64 s[50:51], s[44:45]
	s_mov_b64 s[48:49], s[42:43]
	s_mov_b32 s87, s88
	s_mov_b64 s[90:91], s[92:93]
	s_cbranch_vccnz .LBB0_1143
.LBB0_1095:
	s_add_i32 s62, s62, 1
	s_mul_i32 s10, s62, s63
	s_mul_hi_u32 s11, s62, s33
	s_add_i32 s11, s11, s10
	s_mul_i32 s10, s62, s33
	s_add_u32 s42, s10, s3
	s_addc_u32 s43, s11, s66
	v_cmp_gt_i64_e64 s[10:11], s[42:43], v[174:175]
	s_and_b64 vcc, exec, s[10:11]
	s_cbranch_vccnz .LBB0_1097
	s_cmpk_lt_u32 s42, 0xb00
	s_cbranch_scc0 .Lp8_dec_samp
	s_and_b32 s38, s42, 7
	s_mulk_i32 s38, 0x160
	s_lshr_b32 s39, s42, 3
	s_add_i32 s38, s38, s39
	s_lshr_b32 s39, s38, 3
	s_mul_hi_u32 s39, s39, 0xba2e8ba3
	s_lshr_b32 s39, s39, 3
	s_mul_i32 s41, s39, 0x58
	s_sub_i32 s38, s38, s41
	s_lshl_b32 s39, s39, 1
	s_and_b32 s41, s38, 1
	s_add_i32 s40, s39, s41
	s_lshr_b32 s38, s38, 1
	s_mov_b32 s88, 28
	s_mov_b32 s89, 0
	s_branch .LBB0_1097
.Lp8_dec_samp:
	s_sub_i32 s38, s42, 0xb00
	s_and_b32 s89, s38, 1
	s_bfe_u32 s40, s38, 0x10001
	s_add_i32 s40, s40, 64
	s_lshr_b32 s38, s38, 2
	s_mov_b32 s88, 12
	s_mul_i32 s92, s89, 0x1600000
	s_add_u32 s92, s28, s92
	s_addc_u32 s93, s29, 0
	s_lshl_b32 s89, s89, 11
.LBB0_1097:
	s_ashr_i32 s41, s40, 31
	v_cmp_lt_i64_e32 vcc, s[42:43], v[172:173]
	s_lshl_b64 s[42:43], s[40:41], 20
	s_add_u32 s42, s57, s42
	s_addc_u32 s43, s58, s43
	s_add_u32 s42, s42, s89
	s_addc_u32 s43, s43, 0
	s_and_b64 s[44:45], vcc, exec
	s_cselect_b32 s41, s43, s49
	s_cselect_b32 s47, s42, s48
	s_ashr_i32 s39, s38, 31
	s_lshl_b64 s[44:45], s[38:39], 20
	s_add_u32 s44, s18, s44
	s_addc_u32 s45, s19, s45
	s_add_u32 s44, s44, s89
	s_addc_u32 s45, s45, 0
	s_and_b64 s[52:53], vcc, exec
	s_cselect_b32 s39, s45, s51
	s_cselect_b32 s73, s44, s50
	s_add_u32 s48, s48, 0x80080
	s_addc_u32 s49, s49, 0
	s_add_u32 s74, s50, 0x100
	v_mov_b32_e32 v2, 0
	s_addc_u32 s75, s51, 0
	s_mov_b32 s80, -2
	v_mov_b32_e32 v3, v2
	v_mov_b32_e32 v4, v2
	v_mov_b32_e32 v5, v2
	v_mov_b32_e32 v6, v2
	v_mov_b32_e32 v7, v2
	v_mov_b32_e32 v8, v2
	v_mov_b32_e32 v9, v2
	v_mov_b32_e32 v10, v2
	v_mov_b32_e32 v11, v2
	v_mov_b32_e32 v12, v2
	v_mov_b32_e32 v13, v2
	v_mov_b32_e32 v14, v2
	v_mov_b32_e32 v15, v2
	v_mov_b32_e32 v16, v2
	v_mov_b32_e32 v17, v2
	v_mov_b32_e32 v22, v2
	v_mov_b32_e32 v23, v2
	v_mov_b32_e32 v24, v2
	v_mov_b32_e32 v25, v2
	v_mov_b32_e32 v30, v2
	v_mov_b32_e32 v31, v2
	v_mov_b32_e32 v32, v2
	v_mov_b32_e32 v33, v2
	v_mov_b32_e32 v38, v2
	v_mov_b32_e32 v39, v2
	v_mov_b32_e32 v40, v2
	v_mov_b32_e32 v41, v2
	v_mov_b32_e32 v46, v2
	v_mov_b32_e32 v47, v2
	v_mov_b32_e32 v48, v2
	v_mov_b32_e32 v49, v2
	v_mov_b32_e32 v18, v2
	v_mov_b32_e32 v19, v2
	v_mov_b32_e32 v20, v2
	v_mov_b32_e32 v21, v2
	v_mov_b32_e32 v26, v2
	v_mov_b32_e32 v27, v2
	v_mov_b32_e32 v28, v2
	v_mov_b32_e32 v29, v2
	v_mov_b32_e32 v34, v2
	v_mov_b32_e32 v35, v2
	v_mov_b32_e32 v36, v2
	v_mov_b32_e32 v37, v2
	v_mov_b32_e32 v42, v2
	v_mov_b32_e32 v43, v2
	v_mov_b32_e32 v44, v2
	v_mov_b32_e32 v45, v2
	v_mov_b32_e32 v50, v2
	v_mov_b32_e32 v51, v2
	v_mov_b32_e32 v52, v2
	v_mov_b32_e32 v53, v2
	v_mov_b32_e32 v54, v2
	v_mov_b32_e32 v55, v2
	v_mov_b32_e32 v56, v2
	v_mov_b32_e32 v57, v2
	v_mov_b32_e32 v58, v2
	v_mov_b32_e32 v59, v2
	v_mov_b32_e32 v60, v2
	v_mov_b32_e32 v61, v2
	v_mov_b32_e32 v62, v2
	v_mov_b32_e32 v63, v2
	v_mov_b32_e32 v64, v2
	v_mov_b32_e32 v65, v2
	v_mov_b32_e32 v66, v2
	v_mov_b32_e32 v67, v2
	v_mov_b32_e32 v68, v2
	v_mov_b32_e32 v69, v2
	v_mov_b32_e32 v70, v2
	v_mov_b32_e32 v71, v2
	v_mov_b32_e32 v72, v2
	v_mov_b32_e32 v73, v2
	v_mov_b32_e32 v74, v2
	v_mov_b32_e32 v75, v2
	v_mov_b32_e32 v76, v2
	v_mov_b32_e32 v77, v2
	v_mov_b32_e32 v78, v2
	v_mov_b32_e32 v79, v2
	v_mov_b32_e32 v80, v2
	v_mov_b32_e32 v81, v2
	v_mov_b32_e32 v86, v2
	v_mov_b32_e32 v87, v2
	v_mov_b32_e32 v88, v2
	v_mov_b32_e32 v89, v2
	v_mov_b32_e32 v94, v2
	v_mov_b32_e32 v95, v2
	v_mov_b32_e32 v96, v2
	v_mov_b32_e32 v97, v2
	v_mov_b32_e32 v102, v2
	v_mov_b32_e32 v103, v2
	v_mov_b32_e32 v104, v2
	v_mov_b32_e32 v105, v2
	v_mov_b32_e32 v110, v2
	v_mov_b32_e32 v111, v2
	v_mov_b32_e32 v112, v2
	v_mov_b32_e32 v113, v2
	v_mov_b32_e32 v82, v2
	v_mov_b32_e32 v83, v2
	v_mov_b32_e32 v84, v2
	v_mov_b32_e32 v85, v2
	v_mov_b32_e32 v90, v2
	v_mov_b32_e32 v91, v2
	v_mov_b32_e32 v92, v2
	v_mov_b32_e32 v93, v2
	v_mov_b32_e32 v98, v2
	v_mov_b32_e32 v99, v2
	v_mov_b32_e32 v100, v2
	v_mov_b32_e32 v101, v2
	v_mov_b32_e32 v106, v2
	v_mov_b32_e32 v107, v2
	v_mov_b32_e32 v108, v2
	v_mov_b32_e32 v109, v2
	v_mov_b32_e32 v114, v2
	v_mov_b32_e32 v115, v2
	v_mov_b32_e32 v116, v2
	v_mov_b32_e32 v117, v2
	v_mov_b32_e32 v118, v2
	v_mov_b32_e32 v119, v2
	v_mov_b32_e32 v120, v2
	v_mov_b32_e32 v121, v2
	v_mov_b32_e32 v122, v2
	v_mov_b32_e32 v123, v2
	v_mov_b32_e32 v124, v2
	v_mov_b32_e32 v125, v2
	v_mov_b32_e32 v126, v2
	v_mov_b32_e32 v127, v2
	v_mov_b32_e32 v128, v2
	v_mov_b32_e32 v129, v2
.LBB0_1098:
	ds_read_b128 v[130:133], v240
	ds_read_b128 v[134:137], v240 offset:1024
	ds_read_b128 v[138:141], v240 offset:2048
	ds_read_b128 v[142:145], v240 offset:3072
	s_add_u32 s50, s48, 0xfff80080
	s_addc_u32 s51, s49, -1
	s_cmp_eq_u32 s80, s87
	s_cselect_b32 s53, s41, s51
	s_cselect_b32 s52, s47, s50
	s_cselect_b32 s51, s39, s75
	s_cselect_b32 s50, s73, s74
	v_lshl_add_u64 v[168:169], s[48:49], 0, v[166:167]
	s_add_i32 m0, s21, 0xc000
	ds_read_b128 v[146:149], v241
	ds_read_b128 v[150:153], v241 offset:1024
	ds_read_b128 v[154:157], v241 offset:2048
	ds_read_b128 v[158:161], v241 offset:3072
	ds_read_b128 v[176:179], v241 offset:4096
	ds_read_b128 v[180:183], v241 offset:5120
	ds_read_b128 v[184:187], v241 offset:6144
	ds_read_b128 v[188:191], v241 offset:7168
	global_load_lds_dwordx4 v[168:169], off
	v_lshl_add_u64 v[168:169], s[48:49], 0, v[170:171]
	s_add_i32 m0, s21, 0xe000
	s_nop 0
	global_load_lds_dwordx4 v[168:169], off
	s_waitcnt lgkmcnt(8)
	s_barrier
	s_waitcnt lgkmcnt(0)
	s_setprio 1
	s_waitcnt lgkmcnt(0)
	v_mfma_f32_16x16x32_bf16 v[126:129], v[130:133], v[146:149], v[126:129]
	v_mfma_f32_16x16x32_bf16 v[122:125], v[138:141], v[146:149], v[122:125]
	v_mfma_f32_16x16x32_bf16 v[118:121], v[130:133], v[154:157], v[118:121]
	v_mfma_f32_16x16x32_bf16 v[114:117], v[138:141], v[154:157], v[114:117]
	v_mfma_f32_16x16x32_bf16 v[106:109], v[130:133], v[176:179], v[106:109]
	v_mfma_f32_16x16x32_bf16 v[98:101], v[138:141], v[176:179], v[98:101]
	v_mfma_f32_16x16x32_bf16 v[90:93], v[130:133], v[184:187], v[90:93]
	v_mfma_f32_16x16x32_bf16 v[82:85], v[138:141], v[184:187], v[82:85]
	v_mfma_f32_16x16x32_bf16 v[126:129], v[134:137], v[150:153], v[126:129]
	v_mfma_f32_16x16x32_bf16 v[122:125], v[142:145], v[150:153], v[122:125]
	v_mfma_f32_16x16x32_bf16 v[118:121], v[134:137], v[158:161], v[118:121]
	v_mfma_f32_16x16x32_bf16 v[114:117], v[142:145], v[158:161], v[114:117]
	v_mfma_f32_16x16x32_bf16 v[106:109], v[134:137], v[180:183], v[106:109]
	v_mfma_f32_16x16x32_bf16 v[98:101], v[142:145], v[180:183], v[98:101]
	v_mfma_f32_16x16x32_bf16 v[90:93], v[134:137], v[188:191], v[90:93]
	v_mfma_f32_16x16x32_bf16 v[82:85], v[142:145], v[188:191], v[82:85]
	s_setprio 0
	s_barrier
	s_add_i32 s81, s68, s56
	v_lshl_add_u64 v[168:169], s[50:51], 0, v[162:163]
	s_mov_b32 m0, s81
	ds_read_b128 v[192:195], v242
	ds_read_b128 v[196:199], v242 offset:1024
	ds_read_b128 v[200:203], v242 offset:2048
	ds_read_b128 v[204:207], v242 offset:3072
	global_load_lds_dwordx4 v[168:169], off
	v_lshl_add_u64 v[208:209], s[50:51], 0, v[164:165]
	s_add_i32 m0, s81, 0x2000
	s_nop 0
	global_load_lds_dwordx4 v[208:209], off
	s_barrier
	s_waitcnt lgkmcnt(0)
	s_setprio 1
	s_waitcnt lgkmcnt(0)
	v_mfma_f32_16x16x32_bf16 v[110:113], v[192:195], v[146:149], v[110:113]
	v_mfma_f32_16x16x32_bf16 v[102:105], v[200:203], v[146:149], v[102:105]
	v_mfma_f32_16x16x32_bf16 v[94:97], v[192:195], v[154:157], v[94:97]
	v_mfma_f32_16x16x32_bf16 v[86:89], v[200:203], v[154:157], v[86:89]
	v_mfma_f32_16x16x32_bf16 v[78:81], v[192:195], v[176:179], v[78:81]
	v_mfma_f32_16x16x32_bf16 v[74:77], v[200:203], v[176:179], v[74:77]
	v_mfma_f32_16x16x32_bf16 v[70:73], v[192:195], v[184:187], v[70:73]
	v_mfma_f32_16x16x32_bf16 v[66:69], v[200:203], v[184:187], v[66:69]
	v_mfma_f32_16x16x32_bf16 v[110:113], v[196:199], v[150:153], v[110:113]
	v_mfma_f32_16x16x32_bf16 v[102:105], v[204:207], v[150:153], v[102:105]
	v_mfma_f32_16x16x32_bf16 v[94:97], v[196:199], v[158:161], v[94:97]
	v_mfma_f32_16x16x32_bf16 v[86:89], v[204:207], v[158:161], v[86:89]
	v_mfma_f32_16x16x32_bf16 v[78:81], v[196:199], v[180:183], v[78:81]
	v_mfma_f32_16x16x32_bf16 v[74:77], v[204:207], v[180:183], v[74:77]
	v_mfma_f32_16x16x32_bf16 v[70:73], v[196:199], v[188:191], v[70:73]
	v_mfma_f32_16x16x32_bf16 v[66:69], v[204:207], v[188:191], v[66:69]
	s_setprio 0
	s_mov_b32 m0, s21
	v_lshl_add_u64 v[210:211], s[52:53], 0, v[162:163]
	s_barrier
	ds_read_b128 v[146:149], v241 offset:16384
	ds_read_b128 v[150:153], v241 offset:17408
	ds_read_b128 v[154:157], v241 offset:18432
	ds_read_b128 v[158:161], v241 offset:19456
	ds_read_b128 v[176:179], v241 offset:20480
	ds_read_b128 v[180:183], v241 offset:21504
	ds_read_b128 v[184:187], v241 offset:22528
	ds_read_b128 v[188:191], v241 offset:23552
	global_load_lds_dwordx4 v[210:211], off
	v_lshl_add_u64 v[212:213], s[52:53], 0, v[164:165]
	s_mov_b32 m0, s59
	s_nop 0
	global_load_lds_dwordx4 v[212:213], off
	s_barrier
	s_waitcnt lgkmcnt(0)
	s_setprio 1
	s_waitcnt lgkmcnt(0)
	v_mfma_f32_16x16x32_bf16 v[62:65], v[130:133], v[146:149], v[62:65]
	v_mfma_f32_16x16x32_bf16 v[58:61], v[138:141], v[146:149], v[58:61]
	v_mfma_f32_16x16x32_bf16 v[54:57], v[130:133], v[154:157], v[54:57]
	v_mfma_f32_16x16x32_bf16 v[50:53], v[138:141], v[154:157], v[50:53]
	v_mfma_f32_16x16x32_bf16 v[42:45], v[130:133], v[176:179], v[42:45]
	v_mfma_f32_16x16x32_bf16 v[34:37], v[138:141], v[176:179], v[34:37]
	v_mfma_f32_16x16x32_bf16 v[26:29], v[130:133], v[184:187], v[26:29]
	v_mfma_f32_16x16x32_bf16 v[18:21], v[138:141], v[184:187], v[18:21]
	v_mfma_f32_16x16x32_bf16 v[62:65], v[134:137], v[150:153], v[62:65]
	v_mfma_f32_16x16x32_bf16 v[58:61], v[142:145], v[150:153], v[58:61]
	v_mfma_f32_16x16x32_bf16 v[54:57], v[134:137], v[158:161], v[54:57]
	v_mfma_f32_16x16x32_bf16 v[50:53], v[142:145], v[158:161], v[50:53]
	v_mfma_f32_16x16x32_bf16 v[42:45], v[134:137], v[180:183], v[42:45]
	v_mfma_f32_16x16x32_bf16 v[34:37], v[142:145], v[180:183], v[34:37]
	v_mfma_f32_16x16x32_bf16 v[26:29], v[134:137], v[188:191], v[26:29]
	v_mfma_f32_16x16x32_bf16 v[18:21], v[142:145], v[188:191], v[18:21]
	s_setprio 0
	s_barrier
	s_add_u32 s82, s50, 0x80000
	s_addc_u32 s83, s51, 0
	s_add_i32 s81, s69, s56
	v_lshl_add_u64 v[130:131], s[82:83], 0, v[162:163]
	s_mov_b32 m0, s81
	s_nop 0
	global_load_lds_dwordx4 v[130:131], off
	v_lshl_add_u64 v[130:131], s[82:83], 0, v[164:165]
	s_add_i32 m0, s81, 0x2000
	s_nop 0
	global_load_lds_dwordx4 v[130:131], off
	s_waitcnt vmcnt(6)
	s_barrier
	s_setprio 1
	v_mfma_f32_16x16x32_bf16 v[46:49], v[192:195], v[146:149], v[46:49]
	v_mfma_f32_16x16x32_bf16 v[38:41], v[200:203], v[146:149], v[38:41]
	v_mfma_f32_16x16x32_bf16 v[30:33], v[192:195], v[154:157], v[30:33]
	v_mfma_f32_16x16x32_bf16 v[22:25], v[200:203], v[154:157], v[22:25]
	v_mfma_f32_16x16x32_bf16 v[14:17], v[192:195], v[176:179], v[14:17]
	v_mfma_f32_16x16x32_bf16 v[10:13], v[200:203], v[176:179], v[10:13]
	v_mfma_f32_16x16x32_bf16 v[6:9], v[192:195], v[184:187], v[6:9]
	v_mfma_f32_16x16x32_bf16 v[2:5], v[200:203], v[184:187], v[2:5]
	v_mfma_f32_16x16x32_bf16 v[46:49], v[196:199], v[150:153], v[46:49]
	v_mfma_f32_16x16x32_bf16 v[38:41], v[204:207], v[150:153], v[38:41]
	v_mfma_f32_16x16x32_bf16 v[30:33], v[196:199], v[158:161], v[30:33]
	v_mfma_f32_16x16x32_bf16 v[22:25], v[204:207], v[158:161], v[22:25]
	v_mfma_f32_16x16x32_bf16 v[14:17], v[196:199], v[180:183], v[14:17]
	v_mfma_f32_16x16x32_bf16 v[10:13], v[204:207], v[180:183], v[10:13]
	v_mfma_f32_16x16x32_bf16 v[6:9], v[196:199], v[188:191], v[6:9]
	v_mfma_f32_16x16x32_bf16 v[2:5], v[204:207], v[188:191], v[2:5]
	s_setprio 0
	s_add_i32 s81, 0, 0x18000
	v_add_u32_e32 v142, s81, v236
	s_barrier
	ds_read_b128 v[130:133], v142
	ds_read_b128 v[134:137], v142 offset:1024
	ds_read_b128 v[138:141], v142 offset:2048
	ds_read_b128 v[142:145], v142 offset:3072
	s_add_u32 s52, s52, 0x80000
	s_addc_u32 s53, s53, 0
	s_mov_b32 m0, s60
	v_lshl_add_u64 v[192:193], s[52:53], 0, v[162:163]
	ds_read_b128 v[146:149], v241 offset:32768
	ds_read_b128 v[150:153], v241 offset:33792
	ds_read_b128 v[154:157], v241 offset:34816
	ds_read_b128 v[158:161], v241 offset:35840
	ds_read_b128 v[176:179], v241 offset:36864
	ds_read_b128 v[180:183], v241 offset:37888
	ds_read_b128 v[184:187], v241 offset:38912
	ds_read_b128 v[188:191], v241 offset:39936
	global_load_lds_dwordx4 v[192:193], off
	v_lshl_add_u64 v[192:193], s[52:53], 0, v[164:165]
	s_mov_b32 m0, s61
	s_nop 0
	global_load_lds_dwordx4 v[192:193], off
	s_waitcnt lgkmcnt(8)
	s_barrier
	s_waitcnt lgkmcnt(0)
	s_setprio 1
	s_waitcnt lgkmcnt(0)
	v_mfma_f32_16x16x32_bf16 v[126:129], v[130:133], v[146:149], v[126:129]
	v_mfma_f32_16x16x32_bf16 v[122:125], v[138:141], v[146:149], v[122:125]
	v_mfma_f32_16x16x32_bf16 v[118:121], v[130:133], v[154:157], v[118:121]
	v_mfma_f32_16x16x32_bf16 v[114:117], v[138:141], v[154:157], v[114:117]
	v_mfma_f32_16x16x32_bf16 v[106:109], v[130:133], v[176:179], v[106:109]
	v_mfma_f32_16x16x32_bf16 v[98:101], v[138:141], v[176:179], v[98:101]
	v_mfma_f32_16x16x32_bf16 v[90:93], v[130:133], v[184:187], v[90:93]
	v_mfma_f32_16x16x32_bf16 v[82:85], v[138:141], v[184:187], v[82:85]
	v_mfma_f32_16x16x32_bf16 v[126:129], v[134:137], v[150:153], v[126:129]
	v_mfma_f32_16x16x32_bf16 v[122:125], v[142:145], v[150:153], v[122:125]
	v_mfma_f32_16x16x32_bf16 v[118:121], v[134:137], v[158:161], v[118:121]
	v_mfma_f32_16x16x32_bf16 v[114:117], v[142:145], v[158:161], v[114:117]
	v_mfma_f32_16x16x32_bf16 v[106:109], v[134:137], v[180:183], v[106:109]
	v_mfma_f32_16x16x32_bf16 v[98:101], v[142:145], v[180:183], v[98:101]
	v_mfma_f32_16x16x32_bf16 v[90:93], v[134:137], v[188:191], v[90:93]
	v_mfma_f32_16x16x32_bf16 v[82:85], v[142:145], v[188:191], v[82:85]
	s_setprio 0
	s_barrier
	s_add_i32 s52, 0, 0x1c000
	s_add_i32 s53, s81, s56
	v_add_u32_e32 v204, s52, v236
	v_lshl_add_u64 v[168:169], v[168:169], 0, s[36:37]
	s_mov_b32 m0, s53
	ds_read_b128 v[192:195], v204
	ds_read_b128 v[196:199], v204 offset:1024
	ds_read_b128 v[200:203], v204 offset:2048
	ds_read_b128 v[204:207], v204 offset:3072
	global_load_lds_dwordx4 v[168:169], off
	v_lshl_add_u64 v[168:169], v[208:209], 0, s[36:37]
	s_add_i32 m0, s53, 0x2000
	s_nop 0
	global_load_lds_dwordx4 v[168:169], off
	s_barrier
	s_waitcnt lgkmcnt(0)
	s_setprio 1
	s_waitcnt lgkmcnt(0)
	v_mfma_f32_16x16x32_bf16 v[110:113], v[192:195], v[146:149], v[110:113]
	v_mfma_f32_16x16x32_bf16 v[102:105], v[200:203], v[146:149], v[102:105]
	v_mfma_f32_16x16x32_bf16 v[94:97], v[192:195], v[154:157], v[94:97]
	v_mfma_f32_16x16x32_bf16 v[86:89], v[200:203], v[154:157], v[86:89]
	v_mfma_f32_16x16x32_bf16 v[78:81], v[192:195], v[176:179], v[78:81]
	v_mfma_f32_16x16x32_bf16 v[74:77], v[200:203], v[176:179], v[74:77]
	v_mfma_f32_16x16x32_bf16 v[70:73], v[192:195], v[184:187], v[70:73]
	v_mfma_f32_16x16x32_bf16 v[66:69], v[200:203], v[184:187], v[66:69]
	v_mfma_f32_16x16x32_bf16 v[110:113], v[196:199], v[150:153], v[110:113]
	v_mfma_f32_16x16x32_bf16 v[102:105], v[204:207], v[150:153], v[102:105]
	v_mfma_f32_16x16x32_bf16 v[94:97], v[196:199], v[158:161], v[94:97]
	v_mfma_f32_16x16x32_bf16 v[86:89], v[204:207], v[158:161], v[86:89]
	v_mfma_f32_16x16x32_bf16 v[78:81], v[196:199], v[180:183], v[78:81]
	v_mfma_f32_16x16x32_bf16 v[74:77], v[204:207], v[180:183], v[74:77]
	v_mfma_f32_16x16x32_bf16 v[70:73], v[196:199], v[188:191], v[70:73]
	v_mfma_f32_16x16x32_bf16 v[66:69], v[204:207], v[188:191], v[66:69]
	s_setprio 0
	s_mov_b32 m0, s64
	v_lshl_add_u64 v[168:169], v[210:211], 0, s[36:37]
	s_barrier
	ds_read_b128 v[146:149], v241 offset:49152
	ds_read_b128 v[150:153], v241 offset:50176
	ds_read_b128 v[154:157], v241 offset:51200
	ds_read_b128 v[158:161], v241 offset:52224
	ds_read_b128 v[176:179], v241 offset:53248
	ds_read_b128 v[180:183], v241 offset:54272
	ds_read_b128 v[184:187], v241 offset:55296
	ds_read_b128 v[188:191], v241 offset:56320
	global_load_lds_dwordx4 v[168:169], off
	v_lshl_add_u64 v[168:169], v[212:213], 0, s[36:37]
	s_mov_b32 m0, s65
	s_nop 0
	global_load_lds_dwordx4 v[168:169], off
	s_barrier
	s_waitcnt lgkmcnt(0)
	s_setprio 1
	s_waitcnt lgkmcnt(0)
	v_mfma_f32_16x16x32_bf16 v[62:65], v[130:133], v[146:149], v[62:65]
	v_mfma_f32_16x16x32_bf16 v[58:61], v[138:141], v[146:149], v[58:61]
	v_mfma_f32_16x16x32_bf16 v[54:57], v[130:133], v[154:157], v[54:57]
	v_mfma_f32_16x16x32_bf16 v[50:53], v[138:141], v[154:157], v[50:53]
	v_mfma_f32_16x16x32_bf16 v[42:45], v[130:133], v[176:179], v[42:45]
	v_mfma_f32_16x16x32_bf16 v[34:37], v[138:141], v[176:179], v[34:37]
	v_mfma_f32_16x16x32_bf16 v[26:29], v[130:133], v[184:187], v[26:29]
	v_mfma_f32_16x16x32_bf16 v[18:21], v[138:141], v[184:187], v[18:21]
	v_mfma_f32_16x16x32_bf16 v[62:65], v[134:137], v[150:153], v[62:65]
	v_mfma_f32_16x16x32_bf16 v[58:61], v[142:145], v[150:153], v[58:61]
	v_mfma_f32_16x16x32_bf16 v[54:57], v[134:137], v[158:161], v[54:57]
	v_mfma_f32_16x16x32_bf16 v[50:53], v[142:145], v[158:161], v[50:53]
	v_mfma_f32_16x16x32_bf16 v[42:45], v[134:137], v[180:183], v[42:45]
	v_mfma_f32_16x16x32_bf16 v[34:37], v[142:145], v[180:183], v[34:37]
	v_mfma_f32_16x16x32_bf16 v[26:29], v[134:137], v[188:191], v[26:29]
	v_mfma_f32_16x16x32_bf16 v[18:21], v[142:145], v[188:191], v[18:21]
	s_setprio 0
	s_barrier
	s_add_u32 s50, s50, 0x80080
	s_addc_u32 s51, s51, 0
	s_add_i32 s52, s52, s56
	v_lshl_add_u64 v[130:131], s[50:51], 0, v[162:163]
	s_mov_b32 m0, s52
	s_nop 0
	global_load_lds_dwordx4 v[130:131], off
	v_lshl_add_u64 v[130:131], s[50:51], 0, v[164:165]
	s_add_i32 m0, s52, 0x2000
	s_nop 0
	global_load_lds_dwordx4 v[130:131], off
	s_waitcnt vmcnt(6)
	s_barrier
	s_setprio 1
	v_mfma_f32_16x16x32_bf16 v[46:49], v[192:195], v[146:149], v[46:49]
	v_mfma_f32_16x16x32_bf16 v[38:41], v[200:203], v[146:149], v[38:41]
	v_mfma_f32_16x16x32_bf16 v[30:33], v[192:195], v[154:157], v[30:33]
	v_mfma_f32_16x16x32_bf16 v[22:25], v[200:203], v[154:157], v[22:25]
	v_mfma_f32_16x16x32_bf16 v[14:17], v[192:195], v[176:179], v[14:17]
	v_mfma_f32_16x16x32_bf16 v[10:13], v[200:203], v[176:179], v[10:13]
	v_mfma_f32_16x16x32_bf16 v[6:9], v[192:195], v[184:187], v[6:9]
	v_mfma_f32_16x16x32_bf16 v[2:5], v[200:203], v[184:187], v[2:5]
	v_mfma_f32_16x16x32_bf16 v[46:49], v[196:199], v[150:153], v[46:49]
	v_mfma_f32_16x16x32_bf16 v[38:41], v[204:207], v[150:153], v[38:41]
	v_mfma_f32_16x16x32_bf16 v[30:33], v[196:199], v[158:161], v[30:33]
	v_mfma_f32_16x16x32_bf16 v[22:25], v[204:207], v[158:161], v[22:25]
	v_mfma_f32_16x16x32_bf16 v[14:17], v[196:199], v[180:183], v[14:17]
	v_mfma_f32_16x16x32_bf16 v[10:13], v[204:207], v[180:183], v[10:13]
	v_mfma_f32_16x16x32_bf16 v[6:9], v[196:199], v[188:191], v[6:9]
	v_mfma_f32_16x16x32_bf16 v[2:5], v[204:207], v[188:191], v[2:5]
	s_setprio 0
	s_add_i32 s80, s80, 2
	s_add_u32 s48, s48, 0x100
	s_addc_u32 s49, s49, 0
	s_add_u32 s74, s74, 0x100
	s_addc_u32 s75, s75, 0
	s_cmp_gt_u32 s80, s87
	s_barrier
	s_cbranch_scc0 .LBB0_1098
	v_lshl_or_b32 v176, s46, 7, v239
	s_cmp_gt_i32 s20, 63
	v_ashrrev_i32_e32 v177, 31, v176
	s_mov_b64 s[46:47], -1
	s_cbranch_scc1 .LBB0_1141
	v_lshlrev_b64 v[130:131], 2, v[176:177]
	v_lshl_add_u64 v[186:187], s[12:13], 0, v[130:131]
	v_add_co_u32_e32 v146, vcc, 0x5000, v186
	v_lshl_add_u64 v[184:185], s[30:31], 0, v[130:131]
	s_nop 0
	v_addc_co_u32_e32 v147, vcc, 0, v187, vcc
	v_add_co_u32_e32 v150, vcc, 0x5000, v184
	v_lshl_add_u64 v[182:183], s[34:35], 0, v[130:131]
	v_lshl_add_u64 v[180:181], s[14:15], 0, v[130:131]
	v_addc_co_u32_e32 v151, vcc, 0, v185, vcc
	global_load_dwordx4 v[134:137], v[186:187], off
	global_load_dwordx4 v[142:145], v[184:185], off
	global_load_dwordx4 v[138:141], v[182:183], off
	global_load_dwordx4 v[130:133], v[180:181], off
	s_nop 0
	global_load_dwordx4 v[146:149], v[146:147], off offset:2048
	s_nop 0
	global_load_dwordx4 v[154:157], v[150:151], off offset:2048
	v_add_co_u32_e32 v150, vcc, 0x5000, v182
	s_lshl_b32 s39, s20, 2
	s_nop 0
	v_addc_co_u32_e32 v151, vcc, 0, v183, vcc
	global_load_dwordx4 v[158:161], v[150:151], off offset:2048
	v_add_co_u32_e32 v150, vcc, 0x5000, v180
	s_add_i32 s39, s39, s55
	s_nop 0
	v_addc_co_u32_e32 v151, vcc, 0, v181, vcc
	global_load_dwordx4 v[150:153], v[150:151], off offset:2048
	s_lshl_b32 s41, s39, 1
	v_add_u32_e32 v168, s41, v1
	v_mad_i64_i32 v[168:169], s[46:47], v168, s71, 0
	v_lshl_add_u64 v[168:169], s[24:25], 0, v[168:169]
	v_mov_b32_dpp v206, v126 row_shr:1 row_mask:0xf bank_mask:0xf bound_ctrl:1
	v_mov_b32_dpp v188, v126 row_shr:2 row_mask:0xf bank_mask:0xf bound_ctrl:1
	v_mov_b32_dpp v200, v126 row_shl:15 row_mask:0xf bank_mask:0xf bound_ctrl:1
	v_mov_b32_dpp v198, v126 row_shl:14 row_mask:0xf bank_mask:0xf bound_ctrl:1
	v_mov_b32_dpp v207, v127 row_shr:1 row_mask:0xf bank_mask:0xf bound_ctrl:1
	v_mov_b32_dpp v189, v127 row_shr:2 row_mask:0xf bank_mask:0xf bound_ctrl:1
	v_mov_b32_dpp v201, v127 row_shl:15 row_mask:0xf bank_mask:0xf bound_ctrl:1
	v_mov_b32_dpp v199, v127 row_shl:14 row_mask:0xf bank_mask:0xf bound_ctrl:1
	v_mov_b32_dpp v210, v128 row_shr:1 row_mask:0xf bank_mask:0xf bound_ctrl:1
	v_mov_b32_dpp v208, v128 row_shr:2 row_mask:0xf bank_mask:0xf bound_ctrl:1
	v_mov_b32_dpp v204, v128 row_shl:15 row_mask:0xf bank_mask:0xf bound_ctrl:1
	v_mov_b32_dpp v202, v128 row_shl:14 row_mask:0xf bank_mask:0xf bound_ctrl:1
	v_mov_b32_dpp v211, v129 row_shr:1 row_mask:0xf bank_mask:0xf bound_ctrl:1
	v_mov_b32_dpp v209, v129 row_shr:2 row_mask:0xf bank_mask:0xf bound_ctrl:1
	v_mov_b32_dpp v205, v129 row_shl:15 row_mask:0xf bank_mask:0xf bound_ctrl:1
	v_mov_b32_dpp v203, v129 row_shl:14 row_mask:0xf bank_mask:0xf bound_ctrl:1
	v_lshl_add_u64 v[178:179], v[176:177], 2, v[168:169]
	s_and_saveexec_b64 s[46:47], s[4:5]
	s_cbranch_execz .LBB0_1102
	global_store_dwordx4 v[178:179], v[126:129], off

.LBB0_1141:
	s_and_b64 vcc, exec, s[46:47]
	s_cbranch_vccz .LBB0_1094
	v_lshl_add_u32 v136, s20, 8, v238
	v_mov_b64_e32 v[130:131], s[90:91]
	v_mad_i64_i32 v[132:133], s[46:47], v136, s71, v[130:131]
	v_lshlrev_b64 v[134:135], 2, v[176:177]
	v_lshl_add_u64 v[132:133], v[132:133], 0, v[134:135]
	global_store_dwordx4 v[132:133], v[126:129], off
	global_store_dwordx4 v[132:133], v[122:125], off offset:64
	s_nop 1
	v_add_co_u32_e32 v122, vcc, 0x5000, v132
	s_nop 1
	v_addc_co_u32_e32 v123, vcc, 0, v133, vcc
	global_store_dwordx4 v[122:123], v[110:113], off offset:2048
	global_store_dwordx4 v[122:123], v[102:105], off offset:2112
	s_nop 1
	v_or_b32_e32 v102, 16, v136
	v_mad_i64_i32 v[102:103], s[46:47], v102, s71, v[130:131]
	v_lshl_add_u64 v[102:103], v[102:103], 0, v[134:135]
	global_store_dwordx4 v[102:103], v[118:121], off
	global_store_dwordx4 v[102:103], v[114:117], off offset:64
	v_add_co_u32_e32 v102, vcc, 0x5000, v102
	s_nop 1
	v_addc_co_u32_e32 v103, vcc, 0, v103, vcc
	global_store_dwordx4 v[102:103], v[94:97], off offset:2048
	global_store_dwordx4 v[102:103], v[86:89], off offset:2112
	s_nop 1
	v_or_b32_e32 v86, 32, v136
	v_mad_i64_i32 v[86:87], s[46:47], v86, s71, v[130:131]
	v_lshl_add_u64 v[86:87], v[86:87], 0, v[134:135]
	global_store_dwordx4 v[86:87], v[106:109], off
	global_store_dwordx4 v[86:87], v[98:101], off offset:64
	v_add_co_u32_e32 v86, vcc, 0x5000, v86
	s_nop 1
	v_addc_co_u32_e32 v87, vcc, 0, v87, vcc
	global_store_dwordx4 v[86:87], v[78:81], off offset:2048
	global_store_dwordx4 v[86:87], v[74:77], off offset:2112
	s_nop 1
	v_or_b32_e32 v74, 48, v136
	v_mad_i64_i32 v[74:75], s[46:47], v74, s71, v[130:131]
	v_lshl_add_u64 v[74:75], v[74:75], 0, v[134:135]
	global_store_dwordx4 v[74:75], v[90:93], off
	global_store_dwordx4 v[74:75], v[82:85], off offset:64
	v_add_co_u32_e32 v74, vcc, 0x5000, v74
	s_nop 1
	v_addc_co_u32_e32 v75, vcc, 0, v75, vcc
	global_store_dwordx4 v[74:75], v[70:73], off offset:2048
	global_store_dwordx4 v[74:75], v[66:69], off offset:2112
	s_nop 1
	v_add_u32_e32 v66, 0x80, v136
	v_mad_i64_i32 v[66:67], s[46:47], v66, s71, v[130:131]
	v_lshl_add_u64 v[66:67], v[66:67], 0, v[134:135]
	global_store_dwordx4 v[66:67], v[62:65], off
	global_store_dwordx4 v[66:67], v[58:61], off offset:64
	s_nop 1
	v_add_co_u32_e32 v58, vcc, 0x5000, v66
	s_nop 1
	v_addc_co_u32_e32 v59, vcc, 0, v67, vcc
	global_store_dwordx4 v[58:59], v[46:49], off offset:2048
	global_store_dwordx4 v[58:59], v[38:41], off offset:2112
	s_nop 1
	v_add_u32_e32 v38, 0x90, v136
	v_mad_i64_i32 v[38:39], s[46:47], v38, s71, v[130:131]
	v_lshl_add_u64 v[38:39], v[38:39], 0, v[134:135]
	global_store_dwordx4 v[38:39], v[54:57], off
	global_store_dwordx4 v[38:39], v[50:53], off offset:64
	v_add_co_u32_e32 v38, vcc, 0x5000, v38
	s_nop 1
	v_addc_co_u32_e32 v39, vcc, 0, v39, vcc
	global_store_dwordx4 v[38:39], v[30:33], off offset:2048
	global_store_dwordx4 v[38:39], v[22:25], off offset:2112
	s_nop 1
	v_add_u32_e32 v22, 0xa0, v136
	v_mad_i64_i32 v[22:23], s[46:47], v22, s71, v[130:131]
	v_lshl_add_u64 v[22:23], v[22:23], 0, v[134:135]
	global_store_dwordx4 v[22:23], v[42:45], off
	global_store_dwordx4 v[22:23], v[34:37], off offset:64
	v_add_co_u32_e32 v22, vcc, 0x5000, v22
	s_nop 1
	v_addc_co_u32_e32 v23, vcc, 0, v23, vcc
	global_store_dwordx4 v[22:23], v[14:17], off offset:2048
	global_store_dwordx4 v[22:23], v[10:13], off offset:2112
	s_nop 1
	v_add_u32_e32 v10, 0xb0, v136
	v_mad_i64_i32 v[10:11], s[46:47], v10, s71, v[130:131]
	v_lshl_add_u64 v[10:11], v[10:11], 0, v[134:135]
	global_store_dwordx4 v[10:11], v[26:29], off
	global_store_dwordx4 v[10:11], v[18:21], off offset:64
	v_add_co_u32_e32 v10, vcc, 0x5000, v10
	s_nop 1
	v_addc_co_u32_e32 v11, vcc, 0, v11, vcc
	global_store_dwordx4 v[10:11], v[6:9], off offset:2048
	global_store_dwordx4 v[10:11], v[2:5], off offset:2112
	s_branch .LBB0_1094

.LBB0_1212:
	s_or_b64 exec, exec, s[34:35]
	s_mov_b64 s[6:7], 0
	s_mov_b32 s84, 0x1600000
	s_mov_b32 s85, 0
	s_mov_b32 s30, 0x2e8ba2e9
	v_mov_b32_e32 v3, 0
	s_mov_b32 s31, 0xaffff
	v_mov_b32_e32 v4, v54
.LBB0_1213:
	v_mul_hi_i32 v2, v4, s30
	v_lshrrev_b32_e32 v5, 31, v2
	v_ashrrev_i32_e32 v2, 8, v2
	v_add_u32_e32 v5, v2, v5
	v_mul_i32_i24_e32 v2, 0x580, v5
	v_ashrrev_i32_e32 v10, 3, v5
	v_lshlrev_b32_e32 v2, 2, v2
	v_and_b32_e32 v16, 15, v5
	v_add_u32_e32 v8, -1, v5
	v_add_u32_e32 v12, -2, v5
	v_and_b32_e32 v14, 0xfffffe, v10
	v_or_b32_e32 v15, 1, v10
	v_sub_u32_e32 v64, v55, v2
	v_mul_hi_i32_i24_e32 v7, 0xb000, v5
	v_mul_i32_i24_e32 v6, 0xb000, v5
	v_mul_hi_i32_i24_e32 v9, 0xb000, v8
	v_mul_i32_i24_e32 v8, 0xb000, v8
	v_mul_hi_i32_i24_e32 v11, 0xb000, v12
	v_mul_i32_i24_e32 v10, 0xb000, v12
	v_mul_hi_i32_i24_e32 v13, 0xb000, v15
	v_mul_i32_i24_e32 v12, 0xb000, v15
	v_add_u32_e32 v2, v14, v16
	v_ashrrev_i32_e32 v65, 31, v64
	v_lshl_add_u64 v[6:7], s[18:19], 0, v[6:7]
	v_lshl_add_u64 v[8:9], s[18:19], 0, v[8:9]
	v_lshl_add_u64 v[12:13], s[24:25], 0, v[12:13]
	v_cmp_eq_u32_e32 vcc, 0, v16
	s_mov_b64 s[86:87], vcc
	v_mul_hi_i32_i24_e32 v15, 0xb000, v2
	v_mul_i32_i24_e32 v14, 0xb000, v2
	v_add_u32_e32 v2, 0x1600, v64
	v_cmp_lt_u32_e64 s[4:5], 1, v16
	v_lshlrev_b64 v[16:17], 2, v[64:65]
	v_lshl_add_u64 v[10:11], s[18:19], 0, v[10:11]
	v_lshl_add_u64 v[82:83], v[10:11], 0, s[84:85]
	v_lshl_add_u64 v[14:15], s[24:25], 0, v[14:15]
	v_lshl_add_u64 v[80:81], v[8:9], 0, s[84:85]
	v_lshl_add_u64 v[78:79], v[6:7], 0, s[84:85]
	v_cndmask_b32_e32 v9, v9, v13, vcc
	v_cndmask_b32_e32 v8, v8, v12, vcc
	v_lshlrev_b64 v[46:47], 2, v[2:3]
	v_lshl_add_u64 v[18:19], v[6:7], 0, v[16:17]
	v_lshl_add_u64 v[20:21], v[8:9], 0, v[16:17]
	v_cndmask_b32_e64 v49, v15, v11, s[4:5]
	v_cndmask_b32_e64 v48, v14, v10, s[4:5]
	v_lshl_add_u64 v[60:61], v[6:7], 0, v[46:47]
	v_lshl_add_u64 v[62:63], v[8:9], 0, v[46:47]
	v_lshl_add_u64 v[114:115], v[78:79], 0, v[16:17]
	global_load_dwordx4 v[90:93], v[114:115], off
	v_lshl_add_u64 v[114:115], v[80:81], 0, v[16:17]
	global_load_dwordx4 v[94:97], v[114:115], off
	v_lshl_add_u64 v[114:115], v[80:81], 0, v[46:47]
	global_load_dwordx4 v[98:101], v[114:115], off
	v_lshl_add_u64 v[114:115], v[78:79], 0, v[46:47]
	global_load_dwordx4 v[102:105], v[114:115], off
	v_lshl_add_u64 v[114:115], v[82:83], 0, v[16:17]
	global_load_dwordx4 v[106:109], v[114:115], off
	v_lshl_add_u64 v[114:115], v[82:83], 0, v[46:47]
	global_load_dwordx4 v[110:113], v[114:115], off
	global_load_dwordx4 v[6:9], v[18:19], off
	global_load_dwordx4 v[10:13], v[20:21], off
	v_lshl_add_u64 v[50:51], s[26:27], 0, v[16:17]
	v_lshl_add_u64 v[52:53], s[28:29], 0, v[16:17]
	v_lshl_add_u64 v[56:57], s[12:13], 0, v[16:17]
	v_lshl_add_u64 v[58:59], s[14:15], 0, v[16:17]
	v_lshl_add_u64 v[66:67], s[26:27], 0, v[46:47]
	v_lshl_add_u64 v[70:71], s[12:13], 0, v[46:47]
	v_lshl_add_u64 v[68:69], s[28:29], 0, v[46:47]
	v_lshl_add_u64 v[72:73], s[14:15], 0, v[46:47]
	v_lshl_add_u64 v[74:75], v[48:49], 0, v[16:17]
	global_load_dwordx4 v[14:17], v[50:51], off
	global_load_dwordx4 v[18:21], v[52:53], off
	global_load_dwordx4 v[22:25], v[62:63], off
	global_load_dwordx4 v[26:29], v[66:67], off
	global_load_dwordx4 v[30:33], v[68:69], off
	global_load_dwordx4 v[34:37], v[56:57], off
	global_load_dwordx4 v[38:41], v[58:59], off
	global_load_dwordx4 v[42:45], v[60:61], off
	v_lshl_add_u64 v[66:67], v[48:49], 0, v[46:47]
	global_load_dwordx4 v[46:49], v[70:71], off
	global_load_dwordx4 v[50:53], v[74:75], off
	global_load_dwordx4 v[56:59], v[66:67], off
	global_load_dwordx4 v[60:63], v[72:73], off
	v_add_u32_e32 v2, 0x4000, v5
	v_mul_hi_i32_i24_e32 v67, 0x2c00, v2
	v_mul_i32_i24_e32 v66, 0x2c00, v2
	v_add_u32_e32 v4, s3, v4
	v_cmp_lt_i32_e32 vcc, s31, v4
	v_lshl_add_u64 v[66:67], s[10:11], 0, v[66:67]
	s_or_b64 s[6:7], vcc, s[6:7]
	v_add_u32_e32 v55, s38, v55
	v_lshl_add_u64 v[64:65], v[64:65], 1, v[66:67]
	s_waitcnt vmcnt(10)
	v_pk_add_f32 v[6:7], v[6:7], v[90:91]
	v_pk_add_f32 v[8:9], v[8:9], v[92:93]
	s_mov_b64 s[88:89], exec
	s_andn2_b64 exec, exec, s[86:87]
	v_pk_add_f32 v[10:11], v[10:11], v[94:95]
	v_pk_add_f32 v[12:13], v[12:13], v[96:97]
	s_mov_b64 exec, s[88:89]
	v_pk_mul_f32 v[12:13], v[12:13], v[20:21]
	v_pk_mul_f32 v[10:11], v[10:11], v[18:19]
	v_pk_fma_f32 v[8:9], v[8:9], v[16:17], v[12:13]
	v_pk_fma_f32 v[6:7], v[6:7], v[14:15], v[10:11]
	s_waitcnt vmcnt(7)
	s_andn2_b64 exec, exec, s[86:87]
	v_pk_add_f32 v[22:23], v[22:23], v[98:99]
	v_pk_add_f32 v[24:25], v[24:25], v[100:101]
	s_mov_b64 exec, s[88:89]
	v_pk_mul_f32 v[18:19], v[24:25], v[32:33]
	v_pk_mul_f32 v[20:21], v[22:23], v[30:31]
	s_waitcnt vmcnt(2)
	v_pk_add_f32 v[42:43], v[42:43], v[102:103]
	v_pk_add_f32 v[44:45], v[44:45], v[104:105]
	s_and_b64 exec, exec, s[4:5]
	v_pk_add_f32 v[50:51], v[50:51], v[106:107]
	v_pk_add_f32 v[52:53], v[52:53], v[108:109]
	s_mov_b64 exec, s[88:89]
	v_pk_fma_f32 v[8:9], v[52:53], v[36:37], v[8:9]
	v_pk_fma_f32 v[6:7], v[50:51], v[34:35], v[6:7]
	v_pk_add_f32 v[8:9], v[40:41], v[8:9]
	v_pk_add_f32 v[6:7], v[38:39], v[6:7]
	v_mul_f32_e32 v14, 0xbfb8aa3b, v8
	v_mul_f32_e32 v2, 0xbfb8aa3b, v6
	v_mul_f32_e32 v5, 0xbfb8aa3b, v7
	v_mul_f32_e32 v15, 0xbfb8aa3b, v9
	v_exp_f32_e32 v2, v2
	v_exp_f32_e32 v5, v5
	v_exp_f32_e32 v14, v14
	v_exp_f32_e32 v15, v15
	v_add_f32_e32 v2, 1.0, v2
	v_add_f32_e32 v5, 1.0, v5
	v_add_f32_e32 v16, 1.0, v14
	v_add_f32_e32 v17, 1.0, v15
	v_rcp_f32_e32 v14, v2
	v_rcp_f32_e32 v15, v5
	v_rcp_f32_e32 v16, v16
	v_rcp_f32_e32 v17, v17
	v_pk_fma_f32 v[10:11], v[44:45], v[28:29], v[18:19]
	v_pk_fma_f32 v[12:13], v[42:43], v[26:27], v[20:21]
	s_waitcnt vmcnt(1)
	s_and_b64 exec, exec, s[4:5]
	v_pk_add_f32 v[56:57], v[56:57], v[110:111]
	v_pk_add_f32 v[58:59], v[58:59], v[112:113]
	s_mov_b64 exec, s[88:89]
	v_pk_fma_f32 v[10:11], v[58:59], v[48:49], v[10:11]
	v_pk_fma_f32 v[12:13], v[56:57], v[46:47], v[12:13]
	s_waitcnt vmcnt(0)
	v_pk_add_f32 v[10:11], v[62:63], v[10:11]
	v_pk_add_f32 v[12:13], v[60:61], v[12:13]
	v_pk_mul_f32 v[6:7], v[6:7], v[14:15]
	v_pk_mul_f32 v[8:9], v[8:9], v[16:17]
	v_pk_mul_f32 v[6:7], v[6:7], v[12:13]
	v_pk_mul_f32 v[8:9], v[8:9], v[10:11]
	v_cvt_pk_bf16_f32 v6, v6, v7
	v_cvt_pk_bf16_f32 v7, v8, v9
	global_store_dwordx2 v[64:65], v[6:7], off
	s_andn2_b64 exec, exec, s[6:7]
	s_cbranch_execnz .LBB0_1213

.LBB0_1217:
	s_or_b64 exec, exec, s[4:5]
	s_mov_b32 s4, 0x2c000
	v_cmp_gt_i32_e32 vcc, s4, v54
	s_and_saveexec_b64 s[4:5], vcc
	s_cbranch_execz .LBB0_1220
	s_add_u32 s6, s8, 0xa09c000
	v_lshlrev_b32_e32 v1, 2, v1
	s_addc_u32 s7, s9, 0
	v_lshl_add_u32 v1, s2, 11, v1
	s_lshl_b32 s10, s3, 2
	s_mov_b64 s[8:9], 0
	s_mov_b32 s84, 0x1600000
	s_mov_b32 s85, 0
	s_mov_b32 s11, 0x2e8ba2e9
	s_mov_b32 s12, 0x2bfff
.LBB0_1219:
	v_mul_hi_i32 v2, v54, s11
	v_ashrrev_i32_e32 v3, 9, v2
	v_lshrrev_b32_e32 v4, 31, v2
	v_lshrrev_b32_e32 v2, 10, v2
	v_add_u32_e32 v3, v3, v4
	v_add_lshl_u32 v2, v2, v4, 4
	v_mul_i32_i24_e32 v4, 0xb00, v3
	v_and_b32_e32 v3, 1, v3
	v_lshlrev_b32_e32 v4, 2, v4
	v_or3_b32 v3, v2, v3, 14
	v_sub_u32_e32 v2, v1, v4
	v_mul_hi_i32_i24_e32 v5, 0xb000, v3
	v_mul_i32_i24_e32 v4, 0xb000, v3
	v_lshl_add_u64 v[4:5], s[18:19], 0, v[4:5]
	v_ashrrev_i32_e32 v3, 31, v2
	v_lshl_add_u64 v[2:3], v[2:3], 2, v[4:5]
	v_lshl_add_u64 v[8:9], v[2:3], 0, s[84:85]
	global_load_dwordx4 v[8:11], v[8:9], off
	global_load_dwordx4 v[2:5], v[2:3], off
	v_ashrrev_i32_e32 v55, 31, v54
	v_lshl_add_u64 v[6:7], v[54:55], 4, s[6:7]
	v_add_u32_e32 v54, s3, v54
	v_cmp_lt_i32_e32 vcc, s12, v54
	s_or_b64 s[8:9], vcc, s[8:9]
	v_add_u32_e32 v1, s10, v1
	s_waitcnt vmcnt(0)
	v_pk_add_f32 v[2:3], v[2:3], v[8:9]
	v_pk_add_f32 v[4:5], v[4:5], v[10:11]
	global_store_dwordx4 v[6:7], v[2:5], off
	s_andn2_b64 exec, exec, s[8:9]
	s_cbranch_execnz .LBB0_1219
